# v21 + x->xn prep of batches 2,3 moved out of phase 0 into the window of a split-phase in-proj->mixer grid barrier (batches 0,1)
# speedup vs baseline: 1.0255x; 1.0052x over previous
; __device__ __forceinline__ void prep_x(const int wv, const float* __restrict__ x, bf16_t* __restrict__ orbuf) {
;     const int wave = TIDX >> 6, lane = TIDX & 63;
;     const int rstride = gridDim.x * 8;
;     for (int row0 = blockIdx.x * 8 + wave; row0 < MT; row0 += 4 * rstride) {
;         f32x4 v[4][4];
; #pragma unroll
;         for (int q = 0; q < 4; ++q) { const int row = row0 + q * rstride;
;             if (row < MT) {
; #pragma unroll
;                 for (int i = 0; i < 4; ++i) v[q][i] = *(const f32x4*)(x + (size_t)row * DM + i * 256 + lane * 4);
;             } }
.LBB0_55:
	v_mbcnt_lo_u32_b32 v2, -1, 0
	v_mbcnt_hi_u32_b32 v2, -1, v2
	s_mov_b32 s14, 0x8000
	v_add_u32_e32 v2, s53, v2
	v_ashrrev_i32_e32 v3, 6, v2
	v_lshl_add_u32 v78, s66, 3, v3
	v_cmp_gt_i32_e32 vcc, s14, v78
	v_mbcnt_lo_u32_b32 v2, -1, 0
	v_mbcnt_hi_u32_b32 v2, -1, v2
	s_and_saveexec_b64 s[6:7], vcc
	s_cbranch_execz .LBB0_70
	s_load_dwordx2 s[0:1], s[2:3], 0x0
	v_lshlrev_b32_e32 v2, 2, v2
	s_waitcnt lgkmcnt(0)
	s_add_u32 s10, s10, 0x15400000
	v_and_b32_e32 v66, 0xfc, v2
	s_addc_u32 s11, s11, 0
	s_lshl_b32 s15, s54, 3
	v_mov_b32_e32 v69, 0
	v_lshlrev_b32_e32 v68, 2, v66
	v_lshl_add_u64 v[70:71], s[0:1], 0, v[68:69]
	v_bfrev_b32_e32 v3, 0.5
	s_movk_i32 s0, 0x80
	s_add_i32 s19, s15, s15
	v_bitop3_b32 v67, v2, 4, v3 bitop3:0x6c
	v_bitop3_b32 v80, v2, 8, v3 bitop3:0x6c
	v_bitop3_b32 v81, v2, 16, v3 bitop3:0x6c
	v_bitop3_b32 v82, v2, 32, v3 bitop3:0x6c
	v_bitop3_b32 v83, v2, 64, v3 bitop3:0x6c
	v_bitop3_b32 v84, v2, s0, v3 bitop3:0x6c
	s_lshl_b32 s16, s54, 4
	s_mul_i32 s17, s54, 24
	s_mov_b64 s[12:13], 0
	v_mov_b32_e32 v85, 0x358637bd
	s_mov_b32 s18, 0x800000
	s_add_i32 s19, s19, s15
	s_movk_i32 s20, 0x3fff
	s_branch .LBB0_58

; __device__ __forceinline__ unsigned xb_ld(unsigned* p)              { return __hip_atomic_load(p, __ATOMIC_RELAXED, __HIP_MEMORY_SCOPE_AGENT); }
; __device__ __forceinline__ unsigned xb_add(unsigned* p, unsigned v) { return __hip_atomic_fetch_add(p, v, __ATOMIC_RELAXED, __HIP_MEMORY_SCOPE_AGENT); }
; #define XB_SPIN(cond, bar) do { unsigned _sp = 0; while (cond) { __builtin_amdgcn_s_sleep(1); \
;     if ((++_sp & 255u) == 0u) { if (xb_ld(&(bar)[XB_TMO])) break; if (_sp > XB_SPIN_CAP) { atomicAdd(&(bar)[XB_TMO], 1u); break; } } } } while (0)
; __device__ __forceinline__ void xcd_barrier(const int wv, const XcdBarrier& b) {
;     asm volatile("s_waitcnt vmcnt(0)" ::: "memory");
;     __syncthreads();
;     if (TIDX == 0) {
;         unsigned long long barq = (unsigned long long)b.bar; asm volatile("" : "+s"(barq));
;         unsigned* bar = (unsigned*)barq;
;         __builtin_amdgcn_s_waitcnt(0);
;         unsigned nloc = b.st[0], nx = b.st[1];
;         if (nloc == 0u) { xcd_barrier_complete(bar, b.x, nloc, nx); b.st[0] = nloc; b.st[1] = nx; }
;         const unsigned old = xb_add(&bar[XB_XSUB(b.x)], 1u);
;         const unsigned gen = old / nloc;
;         if (old + 1u == (gen + 1u) * nloc) {
;             __builtin_amdgcn_fence(__ATOMIC_RELEASE, "agent");
;             asm volatile("s_waitcnt vmcnt(0)" ::: "memory");
;             const unsigned og = xb_add(&bar[XB_TOP], 1u);
;             const unsigned tg = og / nx;
;             if (og + 1u == (tg + 1u) * nx) xb_add(&bar[XB_TOPGEN], 1u);
;             else XB_SPIN(xb_ld(&bar[XB_TOPGEN]) == tg, bar);
;             __builtin_amdgcn_fence(__ATOMIC_ACQUIRE, "agent");
;             xb_add(&bar[XB_XGEN(b.x)], 1u);
;             asm volatile("s_waitcnt vmcnt(0)" ::: "memory");
;         } else {
;             XB_SPIN(xb_ld(&bar[XB_XGEN(b.x)]) == gen, bar);
.LBB0_281:
	v_lshl_add_u64 v[2:3], v[178:179], 2, s[2:3]
	v_add_co_u32_e32 v8, vcc, 0x1000, v2
	v_cvt_f32_u32_e32 v1, v6
	s_nop 0
	v_addc_co_u32_e32 v9, vcc, 0, v3, vcc
	flat_atomic_add v5, v[8:9], v184 offset:1024 sc0
	v_rcp_iflag_f32_e32 v1, v1
	v_sub_u32_e32 v7, 0, v6
	v_mul_f32_e32 v1, 0x4f7ffffe, v1
	v_cvt_u32_f32_e32 v1, v1
	v_mul_lo_u32 v7, v7, v1
	v_mul_hi_u32 v7, v1, v7
	v_add_u32_e32 v1, v1, v7
	s_waitcnt vmcnt(0) lgkmcnt(0)
	v_mul_hi_u32 v1, v5, v1
	v_mul_lo_u32 v7, v1, v6
	v_sub_u32_e32 v7, v5, v7
	v_cmp_ge_u32_e32 vcc, v7, v6
	v_add_u32_e32 v8, 1, v1
	v_add_u32_e32 v5, 1, v5
	v_cndmask_b32_e32 v1, v1, v8, vcc
	v_sub_u32_e32 v8, v7, v6
	v_cndmask_b32_e32 v7, v7, v8, vcc
	v_cmp_ge_u32_e32 vcc, v7, v6
	v_add_u32_e32 v7, 1, v1
	s_nop 0
	v_cndmask_b32_e32 v1, v1, v7, vcc
	v_mad_u64_u32 v[6:7], s[4:5], v6, v1, v[6:7]
	v_cmp_ne_u32_e32 vcc, v5, v6
	s_and_saveexec_b64 s[4:5], vcc
	s_xor_b64 s[4:5], exec, s[4:5]
	s_cbranch_execz .LBB0_294
	s_cmp_ge_u32 s79, 2
	s_cbranch_scc1 .Lb1_full
	v_add_co_u32_e32 v4, vcc, 0x2400, v2
	s_nop 1
	v_addc_co_u32_e32 v5, vcc, 0, v3, vcc
	s_nop 0
	v_readfirstlane_b32 s98, v4
	v_readfirstlane_b32 s99, v5
	v_readfirstlane_b32 s100, v1
	s_mov_b32 s101, 0x40000
	s_branch .LBB0_294

; __device__ __forceinline__ float shx(float v, int lane, int mask) { return __int_as_float(__builtin_amdgcn_ds_bpermute((lane ^ mask) << 2, __float_as_int(v))); }
; __device__ __forceinline__ unsigned cvt_pk_bf16(float lo, float hi) { unsigned r; asm volatile("v_cvt_pk_bf16_f32 %0, %1, %2" : "=v"(r) : "v"(lo), "v"(hi)); return r; }
; __device__ __forceinline__ void prep_x(const int wv, const float* __restrict__ x, bf16_t* __restrict__ orbuf) {
;     const int wave = TIDX >> 6, lane = TIDX & 63;
;     const int rstride = gridDim.x * 8;
;     for (int row0 = blockIdx.x * 8 + wave; row0 < MT; row0 += 4 * rstride) {
;         f32x4 v[4][4];
; #pragma unroll
;         for (int q = 0; q < 4; ++q) { const int row = row0 + q * rstride;
;             if (row < MT) {
; #pragma unroll
;                 for (int i = 0; i < 4; ++i) v[q][i] = *(const f32x4*)(x + (size_t)row * DM + i * 256 + lane * 4);
;             } }
; #pragma unroll
;         for (int q = 0; q < 4; ++q) { const int row = row0 + q * rstride;
;             if (row < MT) {
;                 const int b = row / TB, r = row % TB;
;                 bf16_t* xo = orbuf + (size_t)b * TB * 2048 + (size_t)r * DM;
;                 float ss = 0.f;
; #pragma unroll
;                 for (int i = 0; i < 4; ++i) ss += v[q][i][0] * v[q][i][0] + v[q][i][1] * v[q][i][1] + v[q][i][2] * v[q][i][2] + v[q][i][3] * v[q][i][3];
; #pragma unroll
;                 for (int o = 1; o < 64; o <<= 1) ss += shx(ss, lane, o);
;                 const float rs = rsqrtf(ss * (1.0f / 1024.0f) + EPS);
; #pragma unroll
;                 for (int i = 0; i < 4; ++i) { u32x2 w; w.x = cvt_pk_bf16(v[q][i][0] * rs, v[q][i][1] * rs); w.y = cvt_pk_bf16(v[q][i][2] * rs, v[q][i][3] * rs); *(u32x2*)(xo + i * 256 + lane * 4) = w; }
;             } }
;     }
.LBB0_310:
	s_or_b64 exec, exec, s[0:1]
	s_waitcnt lgkmcnt(0)
	s_barrier
	s_cmp_ge_u32 s79, 2
	s_cbranch_scc1 .Lxp_skip
	s_add_i32 s21, s79, 2
	s_lshl_b32 s21, s21, 13
	s_mov_b64 s[2:3], s[56:57]
	s_load_dwordx2 s[10:11], s[56:57], 0x70
	s_waitcnt lgkmcnt(0)
.Lxp_55:
	v_mbcnt_lo_u32_b32 v2, -1, 0
	v_mbcnt_hi_u32_b32 v2, -1, v2
	s_mov_b32 s14, 0x8000
	v_add_u32_e32 v2, s53, v2
	v_ashrrev_i32_e32 v3, 6, v2
	v_lshl_add_u32 v78, s66, 3, v3
	v_add_u32_e32 v78, s21, v78
	v_cmp_gt_i32_e32 vcc, s14, v78
	v_mbcnt_lo_u32_b32 v2, -1, 0
	v_mbcnt_hi_u32_b32 v2, -1, v2
	s_and_saveexec_b64 s[6:7], vcc
	s_cbranch_execz .Lxp_70
	s_load_dwordx2 s[0:1], s[2:3], 0x0
	v_lshlrev_b32_e32 v2, 2, v2
	s_waitcnt lgkmcnt(0)
	s_add_u32 s10, s10, 0x15400000
	v_and_b32_e32 v66, 0xfc, v2
	s_addc_u32 s11, s11, 0
	s_lshl_b32 s15, s54, 3
	v_mov_b32_e32 v69, 0
	v_lshlrev_b32_e32 v68, 2, v66
	v_lshl_add_u64 v[70:71], s[0:1], 0, v[68:69]
	v_bfrev_b32_e32 v3, 0.5
	s_movk_i32 s0, 0x80
	s_add_i32 s19, s15, s15
	v_bitop3_b32 v67, v2, 4, v3 bitop3:0x6c
	v_bitop3_b32 v80, v2, 8, v3 bitop3:0x6c
	v_bitop3_b32 v81, v2, 16, v3 bitop3:0x6c
	v_bitop3_b32 v82, v2, 32, v3 bitop3:0x6c
	v_bitop3_b32 v83, v2, 64, v3 bitop3:0x6c
	v_bitop3_b32 v84, v2, s0, v3 bitop3:0x6c
	s_lshl_b32 s16, s54, 4
	s_mul_i32 s17, s54, 24
	s_mov_b64 s[12:13], 0
	v_mov_b32_e32 v85, 0x358637bd
	s_mov_b32 s18, 0x800000
	s_add_i32 s19, s19, s15
	s_add_i32 s20, s21, 0x1fff
	s_branch .Lxp_58

; __device__ __forceinline__ unsigned xb_ld(unsigned* p)              { return __hip_atomic_load(p, __ATOMIC_RELAXED, __HIP_MEMORY_SCOPE_AGENT); }
; #define XB_SPIN(cond, bar) do { unsigned _sp = 0; while (cond) { __builtin_amdgcn_s_sleep(1); \
;     if ((++_sp & 255u) == 0u) { if (xb_ld(&(bar)[XB_TMO])) break; if (_sp > XB_SPIN_CAP) { atomicAdd(&(bar)[XB_TMO], 1u); break; } } } } while (0)
; __device__ __forceinline__ void xcd_barrier(const int wv, const XcdBarrier& b) {
;     ...
;             XB_SPIN(xb_ld(&bar[XB_XGEN(b.x)]) == gen, bar);
;             __builtin_amdgcn_fence(__ATOMIC_ACQUIRE, "agent");
;             asm volatile("s_waitcnt vmcnt(0)" ::: "memory");
.Lxp_70:
	s_or_b64 exec, exec, s[6:7]
	s_cmp_eq_u32 s101, 0
	s_cbranch_scc1 .Lgwb1_done
	v_mov_b32_e32 v222, s98
	v_mov_b32_e32 v223, s99

; __device__ __forceinline__ KParams kparams() { unsigned long long a = (unsigned long long)__builtin_amdgcn_kernarg_segment_ptr(); asm volatile("" : "+s"(a)); return (KParams)a; }
; __global__ void __launch_bounds__(512, 2) mega(Params p_unused) {
;     ...
;         {
;             KParams kp = kparams(); unsigned char* ws = kp->ws;
;             for (int j = blockIdx.x; j < 512; j += gridDim.x) reta_item(wv, lds, ldsb, WSP(bf16_t, WS_R0), WSP(bf16_t, WS_KV), j);
;         }
.Lxp_skip:
.LBB0_366:
	v_readlane_b32 s2, v253, 0
	v_readlane_b32 s3, v253, 1
	s_mov_b64 s[0:1], s[56:57]
	s_andn2_b64 vcc, exec, s[2:3]
	v_cndmask_b32_e64 v1, 0, 1, s[2:3]
	v_cmp_ne_u32_e64 s[4:5], 1, v1
	s_nop 1
	v_writelane_b32 v254, s4, 22
	s_nop 1
	v_writelane_b32 v254, s5, 23
	s_cbranch_vccnz .LBB0_373
	s_load_dwordx2 s[2:3], s[0:1], 0x70
	s_mov_b32 s8, s66
	s_waitcnt lgkmcnt(0)
	s_add_u32 s0, s2, 0x8c00000
	s_addc_u32 s1, s3, 0
	s_add_u32 s6, s2, 0x4c00000
	s_addc_u32 s7, s3, 0
